# P8: next tile's first A load pair issued ahead of the epilogue stores; first K iteration after an epilogue waits with vmcnt(17) so the epilogue stores only need to be complete at its 4th wait
# baseline (speedup 1.0000x reference)
.LBB0_867:
	s_lshl_b32 s12, s12, 5
	s_and_b32 s18, s12, 0x60
	s_mov_b64 s[12:13], 0x80
	s_add_i32 m0, s35, 0x18000
	v_lshl_add_u64 v[6:7], v[6:7], 0, s[12:13]
	s_ashr_i32 s46, s92, 31
	s_lshl_b32 s15, s14, 13
	s_lshl_b32 s19, s18, 7
	s_waitcnt vmcnt(2)
	s_barrier
	global_load_lds_dwordx4 v[6:7], off
	v_lshl_add_u64 v[4:5], v[4:5], 0, s[12:13]
	s_add_i32 m0, s35, 0x1a000
	s_add_i32 s47, s35, 0x8000
	s_add_i32 s48, s35, 0xa000
	global_load_lds_dwordx4 v[4:5], off
	v_lshl_add_u64 v[0:1], v[0:1], 0, s[12:13]
	s_mov_b32 m0, s47
	s_add_u32 s16, s38, 0x40080
	global_load_lds_dwordx4 v[0:1], off
	v_lshl_add_u64 v[0:1], v[2:3], 0, s[12:13]
	s_mov_b32 m0, s48
	s_addc_u32 s17, s39, 0
	global_load_lds_dwordx4 v[0:1], off
	s_add_i32 m0, s35, 0x1c000
	v_lshl_add_u64 v[0:1], s[16:17], 0, v[130:131]
	global_load_lds_dwordx4 v[0:1], off
	v_lshl_add_u64 v[0:1], s[16:17], 0, v[134:135]
	s_add_i32 m0, s35, 0x1e000
	s_sext_i32_i8 s56, s4
	global_load_lds_dwordx4 v[0:1], off
	v_and_b32_e32 v0, 15, v220
	v_lshlrev_b32_e32 v1, 1, v11
	v_lshlrev_b32_e32 v2, 6, v220
	s_movk_i32 s4, 0x3c0
	v_lshlrev_b32_e32 v3, 2, v220
	v_and_or_b32 v2, v2, s4, v1
	v_and_b32_e32 v3, 32, v3
	v_lshl_or_b32 v144, s14, 6, v0
	v_lshl_or_b32 v0, v0, 6, v1
	v_lshlrev_b32_e32 v1, 8, v220
	v_bitop3_b32 v145, s19, v2, v3 bitop3:0xf6
	v_and_b32_e32 v1, 0x38000, v1
	v_lshlrev_b32_e32 v2, 11, v10
	v_or3_b32 v1, v8, v1, v2
	v_add_u32_e32 v136, v1, v9
	v_lshlrev_b32_e32 v1, 4, v12
	s_waitcnt vmcnt(6)
	s_cmpk_lt_u32 s5, 0x100
	v_and_b32_e32 v1, 0x78000, v1
	v_bitop3_b32 v0, v0, s15, v3 bitop3:0xde
	s_cselect_b64 s[14:15], -1, 0
	v_or3_b32 v1, v8, v1, v2
	s_add_i32 s50, 0, 0x10000
	s_add_i32 s51, 0, 0x14000
	s_mov_b32 s49, s92
	v_or_b32_e32 v146, s18, v11
	v_mov_b32_e32 v137, v131
	v_add_u32_e32 v138, v1, v9
	v_mov_b32_e32 v139, v131
	v_add_u32_e32 v147, s50, v145
	v_add_u32_e32 v148, s51, v145
	v_add_u32_e32 v149, 0, v0
	s_add_u32 s16, s78, 0x2000
	s_addc_u32 s17, s79, 0
	s_add_u32 s18, s78, 0x802000
	s_addc_u32 s19, s79, 0
	s_mov_b32 s100, 0
	s_mov_b32 s101, 0
	s_mov_b64 s[98:99], 0x800000
	s_barrier
	s_branch .LBB0_870

.Ldhs8_done:
	ds_read_b128 v[150:153], v147
	ds_read_b128 v[154:157], v147 offset:1024
	ds_read_b128 v[158:161], v147 offset:2048
	ds_read_b128 v[162:165], v147 offset:3072
	ds_read_b128 v[166:169], v148
	ds_read_b128 v[170:173], v148 offset:1024
	ds_read_b128 v[174:177], v148 offset:2048
	ds_read_b128 v[178:181], v148 offset:3072
	s_add_u32 s38, s36, 0xfffc0080
	s_addc_u32 s39, s37, -1
	s_cmp_eq_u32 s61, 12
	s_cselect_b32 s41, s27, s39
	s_cselect_b32 s40, s57, s38
	s_cselect_b32 s39, s25, s60
	s_cselect_b32 s38, s58, s59
	v_lshl_add_u64 v[214:215], s[36:37], 0, v[136:137]
	s_add_i32 m0, s35, 0xc000
	ds_read_b128 v[182:185], v149
	ds_read_b128 v[186:189], v149 offset:1024
	ds_read_b128 v[190:193], v149 offset:2048
	ds_read_b128 v[194:197], v149 offset:3072
	ds_read_b128 v[198:201], v149 offset:4096
	ds_read_b128 v[202:205], v149 offset:5120
	ds_read_b128 v[206:209], v149 offset:6144
	ds_read_b128 v[210:213], v149 offset:7168
	s_cmp_lg_u32 s101, 0
	s_cbranch_scc1 .Lh2a_w1first
	global_load_lds_dwordx4 v[214:215], off
	v_lshl_add_u64 v[214:215], s[36:37], 0, v[138:139]
	s_add_i32 m0, s35, 0xe000
	s_nop 0
	global_load_lds_dwordx4 v[214:215], off
	s_waitcnt vmcnt(9)
.Lh2a_w1join:
	s_waitcnt lgkmcnt(0)
	s_barrier
	s_setprio 1
	s_waitcnt lgkmcnt(0)
	v_mfma_f32_16x16x32_bf16 v[124:127], v[150:153], v[182:185], v[124:127]
	v_mfma_f32_16x16x32_bf16 v[120:123], v[158:161], v[182:185], v[120:123]
	v_mfma_f32_16x16x32_bf16 v[108:111], v[150:153], v[190:193], v[108:111]
	v_mfma_f32_16x16x32_bf16 v[104:107], v[158:161], v[190:193], v[104:107]
	v_mfma_f32_16x16x32_bf16 v[92:95], v[150:153], v[198:201], v[92:95]
	v_mfma_f32_16x16x32_bf16 v[88:91], v[158:161], v[198:201], v[88:91]
	v_mfma_f32_16x16x32_bf16 v[76:79], v[150:153], v[206:209], v[76:79]
	v_mfma_f32_16x16x32_bf16 v[72:75], v[158:161], v[206:209], v[72:75]
	v_mfma_f32_16x16x32_bf16 v[124:127], v[154:157], v[186:189], v[124:127]
	v_mfma_f32_16x16x32_bf16 v[120:123], v[162:165], v[186:189], v[120:123]
	v_mfma_f32_16x16x32_bf16 v[108:111], v[154:157], v[194:197], v[108:111]
	v_mfma_f32_16x16x32_bf16 v[104:107], v[162:165], v[194:197], v[104:107]
	v_mfma_f32_16x16x32_bf16 v[92:95], v[154:157], v[202:205], v[92:95]
	v_mfma_f32_16x16x32_bf16 v[88:91], v[162:165], v[202:205], v[88:91]
	v_mfma_f32_16x16x32_bf16 v[76:79], v[154:157], v[210:213], v[76:79]
	v_mfma_f32_16x16x32_bf16 v[72:75], v[162:165], v[210:213], v[72:75]
	s_setprio 0
	s_setprio 1
	v_mfma_f32_16x16x32_bf16 v[116:119], v[166:169], v[182:185], v[116:119]
	v_mfma_f32_16x16x32_bf16 v[112:115], v[174:177], v[182:185], v[112:115]
	v_mfma_f32_16x16x32_bf16 v[100:103], v[166:169], v[190:193], v[100:103]
	v_mfma_f32_16x16x32_bf16 v[96:99], v[174:177], v[190:193], v[96:99]
	v_mfma_f32_16x16x32_bf16 v[84:87], v[166:169], v[198:201], v[84:87]
	v_mfma_f32_16x16x32_bf16 v[80:83], v[174:177], v[198:201], v[80:83]
	v_mfma_f32_16x16x32_bf16 v[68:71], v[166:169], v[206:209], v[68:71]
	v_mfma_f32_16x16x32_bf16 v[64:67], v[174:177], v[206:209], v[64:67]
	v_mfma_f32_16x16x32_bf16 v[116:119], v[170:173], v[186:189], v[116:119]
	v_mfma_f32_16x16x32_bf16 v[112:115], v[178:181], v[186:189], v[112:115]
	v_mfma_f32_16x16x32_bf16 v[100:103], v[170:173], v[194:197], v[100:103]
	v_mfma_f32_16x16x32_bf16 v[96:99], v[178:181], v[194:197], v[96:99]
	v_mfma_f32_16x16x32_bf16 v[84:87], v[170:173], v[202:205], v[84:87]
	v_mfma_f32_16x16x32_bf16 v[80:83], v[178:181], v[202:205], v[80:83]
	v_mfma_f32_16x16x32_bf16 v[68:71], v[170:173], v[210:213], v[68:71]
	v_mfma_f32_16x16x32_bf16 v[64:67], v[178:181], v[210:213], v[64:67]
	s_setprio 0
	s_barrier
	s_add_i32 s62, s50, s3
	v_lshl_add_u64 v[214:215], s[38:39], 0, v[130:131]
	s_mov_b32 m0, s62
	ds_read_b128 v[182:185], v149 offset:16384
	ds_read_b128 v[186:189], v149 offset:17408
	ds_read_b128 v[190:193], v149 offset:18432
	ds_read_b128 v[194:197], v149 offset:19456
	ds_read_b128 v[198:201], v149 offset:20480
	ds_read_b128 v[202:205], v149 offset:21504
	ds_read_b128 v[206:209], v149 offset:22528
	ds_read_b128 v[210:213], v149 offset:23552
	global_load_lds_dwordx4 v[214:215], off
	s_add_i32 m0, s62, 0x2000
	s_add_u32 s62, s38, 0x40000
	v_lshl_add_u64 v[216:217], s[38:39], 0, v[134:135]
	s_addc_u32 s63, s39, 0
	s_add_i32 s64, s51, s3
	global_load_lds_dwordx4 v[216:217], off
	v_lshl_add_u64 v[218:219], s[62:63], 0, v[130:131]
	s_mov_b32 m0, s64
	v_lshl_add_u64 v[222:223], s[40:41], 0, v[132:133]
	global_load_lds_dwordx4 v[218:219], off
	v_lshl_add_u64 v[218:219], s[62:63], 0, v[134:135]
	s_add_i32 m0, s64, 0x2000
	s_nop 0
	global_load_lds_dwordx4 v[218:219], off
	v_lshl_add_u64 v[218:219], s[40:41], 0, v[128:129]
	s_mov_b32 m0, s35
	s_nop 0
	global_load_lds_dwordx4 v[218:219], off
	s_mov_b32 m0, s42
	s_nop 0
	global_load_lds_dwordx4 v[222:223], off
	s_cmp_lg_u32 s101, 0
	s_cbranch_scc1 .Lh2a_w2first
	s_waitcnt vmcnt(9)
.Lh2a_w2join:
	s_waitcnt lgkmcnt(0)
	s_barrier
	s_setprio 1
	s_waitcnt lgkmcnt(0)
	v_mfma_f32_16x16x32_bf16 v[60:63], v[150:153], v[182:185], v[60:63]
	v_mfma_f32_16x16x32_bf16 v[56:59], v[158:161], v[182:185], v[56:59]
	v_mfma_f32_16x16x32_bf16 v[44:47], v[150:153], v[190:193], v[44:47]
	v_mfma_f32_16x16x32_bf16 v[40:43], v[158:161], v[190:193], v[40:43]
	v_mfma_f32_16x16x32_bf16 v[28:31], v[150:153], v[198:201], v[28:31]
	v_mfma_f32_16x16x32_bf16 v[24:27], v[158:161], v[198:201], v[24:27]
	v_mfma_f32_16x16x32_bf16 v[12:15], v[150:153], v[206:209], v[12:15]
	v_mfma_f32_16x16x32_bf16 v[8:11], v[158:161], v[206:209], v[8:11]
	v_mfma_f32_16x16x32_bf16 v[60:63], v[154:157], v[186:189], v[60:63]
	v_mfma_f32_16x16x32_bf16 v[56:59], v[162:165], v[186:189], v[56:59]
	v_mfma_f32_16x16x32_bf16 v[44:47], v[154:157], v[194:197], v[44:47]
	v_mfma_f32_16x16x32_bf16 v[40:43], v[162:165], v[194:197], v[40:43]
	v_mfma_f32_16x16x32_bf16 v[28:31], v[154:157], v[202:205], v[28:31]
	v_mfma_f32_16x16x32_bf16 v[24:27], v[162:165], v[202:205], v[24:27]
	v_mfma_f32_16x16x32_bf16 v[12:15], v[154:157], v[210:213], v[12:15]
	v_mfma_f32_16x16x32_bf16 v[8:11], v[162:165], v[210:213], v[8:11]
	s_setprio 0
	s_setprio 1
	v_mfma_f32_16x16x32_bf16 v[52:55], v[166:169], v[182:185], v[52:55]
	v_mfma_f32_16x16x32_bf16 v[48:51], v[174:177], v[182:185], v[48:51]
	v_mfma_f32_16x16x32_bf16 v[36:39], v[166:169], v[190:193], v[36:39]
	v_mfma_f32_16x16x32_bf16 v[32:35], v[174:177], v[190:193], v[32:35]
	v_mfma_f32_16x16x32_bf16 v[20:23], v[166:169], v[198:201], v[20:23]
	v_mfma_f32_16x16x32_bf16 v[16:19], v[174:177], v[198:201], v[16:19]
	v_mfma_f32_16x16x32_bf16 v[4:7], v[166:169], v[206:209], v[4:7]
	v_mfma_f32_16x16x32_bf16 v[0:3], v[174:177], v[206:209], v[0:3]
	v_mfma_f32_16x16x32_bf16 v[52:55], v[170:173], v[186:189], v[52:55]
	v_mfma_f32_16x16x32_bf16 v[48:51], v[178:181], v[186:189], v[48:51]
	v_mfma_f32_16x16x32_bf16 v[36:39], v[170:173], v[194:197], v[36:39]
	v_mfma_f32_16x16x32_bf16 v[32:35], v[178:181], v[194:197], v[32:35]
	v_mfma_f32_16x16x32_bf16 v[20:23], v[170:173], v[202:205], v[20:23]
	v_mfma_f32_16x16x32_bf16 v[16:19], v[178:181], v[202:205], v[16:19]
	v_mfma_f32_16x16x32_bf16 v[4:7], v[170:173], v[210:213], v[4:7]
	v_mfma_f32_16x16x32_bf16 v[0:3], v[178:181], v[210:213], v[0:3]
	s_setprio 0
	s_barrier
	s_add_i32 s62, 0, 0x18000
	s_add_i32 s63, 0, 0x1c000
	v_add_u32_e32 v162, s62, v145
	v_add_u32_e32 v178, s63, v145
	ds_read_b128 v[150:153], v162
	ds_read_b128 v[154:157], v162 offset:1024
	ds_read_b128 v[158:161], v162 offset:2048
	ds_read_b128 v[162:165], v162 offset:3072
	ds_read_b128 v[166:169], v178
	ds_read_b128 v[170:173], v178 offset:1024
	ds_read_b128 v[174:177], v178 offset:2048
	ds_read_b128 v[178:181], v178 offset:3072
	s_add_u32 s40, s40, 0x40000
	s_addc_u32 s41, s41, 0
	s_mov_b32 m0, s43
	v_lshl_add_u64 v[224:225], s[40:41], 0, v[128:129]
	ds_read_b128 v[182:185], v149 offset:32768
	ds_read_b128 v[186:189], v149 offset:33792
	ds_read_b128 v[190:193], v149 offset:34816
	ds_read_b128 v[194:197], v149 offset:35840
	ds_read_b128 v[198:201], v149 offset:36864
	ds_read_b128 v[202:205], v149 offset:37888
	ds_read_b128 v[206:209], v149 offset:38912
	ds_read_b128 v[210:213], v149 offset:39936
	global_load_lds_dwordx4 v[224:225], off
	v_lshl_add_u64 v[224:225], s[40:41], 0, v[132:133]
	s_mov_b32 m0, s44
	s_nop 0
	global_load_lds_dwordx4 v[224:225], off
	s_cmp_lg_u32 s101, 0
	s_cbranch_scc1 .Lh2a_w3first
	s_waitcnt vmcnt(8)
.Lh2a_w3join:
	s_waitcnt lgkmcnt(0)
	s_barrier
	s_setprio 1
	s_waitcnt lgkmcnt(0)
	v_mfma_f32_16x16x32_bf16 v[124:127], v[150:153], v[182:185], v[124:127]
	v_mfma_f32_16x16x32_bf16 v[120:123], v[158:161], v[182:185], v[120:123]
	v_mfma_f32_16x16x32_bf16 v[108:111], v[150:153], v[190:193], v[108:111]
	v_mfma_f32_16x16x32_bf16 v[104:107], v[158:161], v[190:193], v[104:107]
	v_mfma_f32_16x16x32_bf16 v[92:95], v[150:153], v[198:201], v[92:95]
	v_mfma_f32_16x16x32_bf16 v[88:91], v[158:161], v[198:201], v[88:91]
	v_mfma_f32_16x16x32_bf16 v[76:79], v[150:153], v[206:209], v[76:79]
	v_mfma_f32_16x16x32_bf16 v[72:75], v[158:161], v[206:209], v[72:75]
	v_mfma_f32_16x16x32_bf16 v[124:127], v[154:157], v[186:189], v[124:127]
	v_mfma_f32_16x16x32_bf16 v[120:123], v[162:165], v[186:189], v[120:123]
	v_mfma_f32_16x16x32_bf16 v[108:111], v[154:157], v[194:197], v[108:111]
	v_mfma_f32_16x16x32_bf16 v[104:107], v[162:165], v[194:197], v[104:107]
	v_mfma_f32_16x16x32_bf16 v[92:95], v[154:157], v[202:205], v[92:95]
	v_mfma_f32_16x16x32_bf16 v[88:91], v[162:165], v[202:205], v[88:91]
	v_mfma_f32_16x16x32_bf16 v[76:79], v[154:157], v[210:213], v[76:79]
	v_mfma_f32_16x16x32_bf16 v[72:75], v[162:165], v[210:213], v[72:75]
	s_setprio 0
	s_setprio 1
	v_mfma_f32_16x16x32_bf16 v[116:119], v[166:169], v[182:185], v[116:119]
	v_mfma_f32_16x16x32_bf16 v[112:115], v[174:177], v[182:185], v[112:115]
	v_mfma_f32_16x16x32_bf16 v[100:103], v[166:169], v[190:193], v[100:103]
	v_mfma_f32_16x16x32_bf16 v[96:99], v[174:177], v[190:193], v[96:99]
	v_mfma_f32_16x16x32_bf16 v[84:87], v[166:169], v[198:201], v[84:87]
	v_mfma_f32_16x16x32_bf16 v[80:83], v[174:177], v[198:201], v[80:83]
	v_mfma_f32_16x16x32_bf16 v[68:71], v[166:169], v[206:209], v[68:71]
	v_mfma_f32_16x16x32_bf16 v[64:67], v[174:177], v[206:209], v[64:67]
	v_mfma_f32_16x16x32_bf16 v[116:119], v[170:173], v[186:189], v[116:119]
	v_mfma_f32_16x16x32_bf16 v[112:115], v[178:181], v[186:189], v[112:115]
	v_mfma_f32_16x16x32_bf16 v[100:103], v[170:173], v[194:197], v[100:103]
	v_mfma_f32_16x16x32_bf16 v[96:99], v[178:181], v[194:197], v[96:99]
	v_mfma_f32_16x16x32_bf16 v[84:87], v[170:173], v[202:205], v[84:87]
	v_mfma_f32_16x16x32_bf16 v[80:83], v[178:181], v[202:205], v[80:83]
	v_mfma_f32_16x16x32_bf16 v[68:71], v[170:173], v[210:213], v[68:71]
	v_mfma_f32_16x16x32_bf16 v[64:67], v[178:181], v[210:213], v[64:67]
	s_setprio 0
	s_barrier
	s_add_i32 s40, s62, s3
	v_lshl_add_u64 v[214:215], v[214:215], 0, s[12:13]
	s_mov_b32 m0, s40
	ds_read_b128 v[182:185], v149 offset:49152
	ds_read_b128 v[186:189], v149 offset:50176
	ds_read_b128 v[190:193], v149 offset:51200
	ds_read_b128 v[194:197], v149 offset:52224
	ds_read_b128 v[198:201], v149 offset:53248
	ds_read_b128 v[202:205], v149 offset:54272
	ds_read_b128 v[206:209], v149 offset:55296
	ds_read_b128 v[210:213], v149 offset:56320
	global_load_lds_dwordx4 v[214:215], off
	s_add_i32 m0, s40, 0x2000
	s_add_u32 s38, s38, 0x40080
	v_lshl_add_u64 v[214:215], v[216:217], 0, s[12:13]
	s_addc_u32 s39, s39, 0
	s_add_i32 s40, s63, s3
	global_load_lds_dwordx4 v[214:215], off
	v_lshl_add_u64 v[214:215], s[38:39], 0, v[130:131]
	s_mov_b32 m0, s40
	s_nop 0
	global_load_lds_dwordx4 v[214:215], off
	v_lshl_add_u64 v[214:215], s[38:39], 0, v[134:135]
	s_add_i32 m0, s40, 0x2000
	s_nop 0
	global_load_lds_dwordx4 v[214:215], off
	v_lshl_add_u64 v[214:215], v[218:219], 0, s[12:13]
	s_mov_b32 m0, s47
	s_nop 0
	global_load_lds_dwordx4 v[214:215], off
	v_lshl_add_u64 v[214:215], v[222:223], 0, s[12:13]
	s_mov_b32 m0, s48
	s_nop 0
	global_load_lds_dwordx4 v[214:215], off
	s_waitcnt vmcnt(8)
	s_waitcnt lgkmcnt(0)
	s_barrier
	s_setprio 1
	s_waitcnt lgkmcnt(0)
	v_mfma_f32_16x16x32_bf16 v[60:63], v[150:153], v[182:185], v[60:63]
	v_mfma_f32_16x16x32_bf16 v[56:59], v[158:161], v[182:185], v[56:59]
	v_mfma_f32_16x16x32_bf16 v[44:47], v[150:153], v[190:193], v[44:47]
	v_mfma_f32_16x16x32_bf16 v[40:43], v[158:161], v[190:193], v[40:43]
	v_mfma_f32_16x16x32_bf16 v[28:31], v[150:153], v[198:201], v[28:31]
	v_mfma_f32_16x16x32_bf16 v[24:27], v[158:161], v[198:201], v[24:27]
	v_mfma_f32_16x16x32_bf16 v[12:15], v[150:153], v[206:209], v[12:15]
	v_mfma_f32_16x16x32_bf16 v[8:11], v[158:161], v[206:209], v[8:11]
	v_mfma_f32_16x16x32_bf16 v[60:63], v[154:157], v[186:189], v[60:63]
	v_mfma_f32_16x16x32_bf16 v[56:59], v[162:165], v[186:189], v[56:59]
	v_mfma_f32_16x16x32_bf16 v[44:47], v[154:157], v[194:197], v[44:47]
	v_mfma_f32_16x16x32_bf16 v[40:43], v[162:165], v[194:197], v[40:43]
	v_mfma_f32_16x16x32_bf16 v[28:31], v[154:157], v[202:205], v[28:31]
	v_mfma_f32_16x16x32_bf16 v[24:27], v[162:165], v[202:205], v[24:27]
	v_mfma_f32_16x16x32_bf16 v[12:15], v[154:157], v[210:213], v[12:15]
	v_mfma_f32_16x16x32_bf16 v[8:11], v[162:165], v[210:213], v[8:11]
	s_setprio 0
	s_setprio 1
	v_mfma_f32_16x16x32_bf16 v[52:55], v[166:169], v[182:185], v[52:55]
	v_mfma_f32_16x16x32_bf16 v[48:51], v[174:177], v[182:185], v[48:51]
	v_mfma_f32_16x16x32_bf16 v[36:39], v[166:169], v[190:193], v[36:39]
	v_mfma_f32_16x16x32_bf16 v[32:35], v[174:177], v[190:193], v[32:35]
	v_mfma_f32_16x16x32_bf16 v[20:23], v[166:169], v[198:201], v[20:23]
	v_mfma_f32_16x16x32_bf16 v[16:19], v[174:177], v[198:201], v[16:19]
	v_mfma_f32_16x16x32_bf16 v[4:7], v[166:169], v[206:209], v[4:7]
	v_mfma_f32_16x16x32_bf16 v[0:3], v[174:177], v[206:209], v[0:3]
	v_mfma_f32_16x16x32_bf16 v[52:55], v[170:173], v[186:189], v[52:55]
	v_mfma_f32_16x16x32_bf16 v[48:51], v[178:181], v[186:189], v[48:51]
	v_mfma_f32_16x16x32_bf16 v[36:39], v[170:173], v[194:197], v[36:39]
	v_mfma_f32_16x16x32_bf16 v[32:35], v[178:181], v[194:197], v[32:35]
	v_mfma_f32_16x16x32_bf16 v[20:23], v[170:173], v[202:205], v[20:23]
	v_mfma_f32_16x16x32_bf16 v[16:19], v[178:181], v[202:205], v[16:19]
	v_mfma_f32_16x16x32_bf16 v[4:7], v[170:173], v[210:213], v[4:7]
	v_mfma_f32_16x16x32_bf16 v[0:3], v[178:181], v[210:213], v[0:3]
	s_setprio 0
	s_barrier
	s_add_i32 s61, s61, 2
	s_add_u32 s36, s36, 0x100
	s_addc_u32 s37, s37, 0
	s_add_u32 s59, s59, 0x100
	s_addc_u32 s60, s60, 0
	s_cmp_gt_u32 s61, 13
	s_cbranch_scc0 .LBB0_877
	s_and_b64 vcc, exec, s[14:15]
	s_cbranch_vccz .LBB0_880
	s_barrier
.LBB0_880:
	s_add_u32 s20, s57, 0x40080
	s_addc_u32 s21, s27, 0
	v_lshl_add_u64 v[214:215], s[20:21], 0, v[136:137]
	s_add_i32 m0, s35, 0xc000
	v_lshl_add_u64 v[216:217], s[20:21], 0, v[138:139]
	global_load_lds_dwordx4 v[214:215], off
	s_add_i32 m0, s35, 0xe000
	s_nop 0
	global_load_lds_dwordx4 v[216:217], off
	s_mov_b32 s101, 1
	v_lshl_add_u32 v150, s34, 8, v144
	v_lshl_or_b32 v152, s56, 8, v146
	v_ashrrev_i32_e32 v151, 31, v150
	v_max_f32_e32 v124, 0, v124
	v_max_f32_e32 v120, 0, v120
	v_max_f32_e32 v125, 0, v125
	v_max_f32_e32 v121, 0, v121
	v_max_f32_e32 v126, 0, v126
	v_max_f32_e32 v127, 0, v127
	v_ashrrev_i32_e32 v153, 31, v152
	v_lshlrev_b64 v[154:155], 6, v[150:151]
	v_pk_mul_f32 v[124:125], v[124:125], v[124:125]
	v_pk_mul_f32 v[120:121], v[120:121], v[120:121]
	v_max_f32_e32 v122, 0, v122
	v_max_f32_e32 v123, 0, v123
	v_pk_mul_f32 v[126:127], v[126:127], v[126:127]
	v_pk_mul_f32 v[156:157], v[122:123], v[122:123]
	v_cvt_pk_bf16_f32 v122, v124, v125
	v_cvt_pk_bf16_f32 v123, v126, v127
	v_cvt_pk_bf16_f32 v124, v120, v121
	v_lshl_add_u64 v[120:121], s[78:79], 0, v[154:155]
	v_and_b32_e32 v126, 0xfe0, v152
	v_and_b32_e32 v127, 31, v152
	v_lshlrev_b32_e32 v126, 16, v126
	v_lshl_or_b32 v126, v127, 1, v126
	v_add_u32_e32 v255, v154, v126
	v_mov_b32_e32 v127, 0
	v_cvt_pk_bf16_f32 v125, v156, v157
	v_lshl_add_u64 v[120:121], v[120:121], 0, v[126:127]
	v_max_f32_e32 v112, 0, v112
	v_max_f32_e32 v113, 0, v113
	global_store_dwordx4 v[120:121], v[122:125], off
	s_nop 1
	v_pk_mul_f32 v[122:123], v[112:113], v[112:113]
	v_max_f32_e32 v114, 0, v114
	v_max_f32_e32 v116, 0, v116
	v_max_f32_e32 v117, 0, v117
	v_max_f32_e32 v112, 0, v118
	v_max_f32_e32 v113, 0, v119
	v_max_f32_e32 v115, 0, v115
	v_pk_mul_f32 v[116:117], v[116:117], v[116:117]
	v_pk_mul_f32 v[118:119], v[112:113], v[112:113]
	v_pk_mul_f32 v[124:125], v[114:115], v[114:115]
	v_cvt_pk_bf16_f32 v112, v116, v117
	v_cvt_pk_bf16_f32 v113, v118, v119
	v_cvt_pk_bf16_f32 v114, v122, v123
	v_cvt_pk_bf16_f32 v115, v124, v125
	v_max_f32_e32 v104, 0, v104
	v_max_f32_e32 v105, 0, v105
	v_lshl_add_u64 v[200:201], v[120:121], 0, s[98:99]
	global_store_dwordx4 v[200:201], v[112:115], off
	s_nop 1
	v_or_b32_e32 v112, 16, v150
	v_pk_mul_f32 v[114:115], v[104:105], v[104:105]
	v_ashrrev_i32_e32 v113, 31, v112
	v_max_f32_e32 v108, 0, v108
	v_max_f32_e32 v109, 0, v109
	v_max_f32_e32 v106, 0, v106
	v_lshlrev_b64 v[112:113], 6, v[112:113]
	v_pk_mul_f32 v[108:109], v[108:109], v[108:109]
	v_max_f32_e32 v104, 0, v110
	v_max_f32_e32 v105, 0, v111
	v_max_f32_e32 v107, 0, v107
	v_pk_mul_f32 v[110:111], v[104:105], v[104:105]
	v_pk_mul_f32 v[116:117], v[106:107], v[106:107]
	v_cvt_pk_bf16_f32 v104, v108, v109
	v_lshl_add_u64 v[108:109], s[78:79], 0, v[112:113]
	v_cvt_pk_bf16_f32 v105, v110, v111
	v_cvt_pk_bf16_f32 v106, v114, v115
	v_cvt_pk_bf16_f32 v107, v116, v117
	v_lshl_add_u64 v[108:109], v[108:109], 0, v[126:127]
	v_max_f32_e32 v96, 0, v96
	v_max_f32_e32 v97, 0, v97
	global_store_dwordx4 v[108:109], v[104:107], off
	s_nop 1
	v_pk_mul_f32 v[104:105], v[96:97], v[96:97]
	v_max_f32_e32 v98, 0, v98
	v_max_f32_e32 v100, 0, v100
	v_max_f32_e32 v101, 0, v101
	v_max_f32_e32 v96, 0, v102
	v_max_f32_e32 v97, 0, v103
	v_max_f32_e32 v99, 0, v99
	v_pk_mul_f32 v[100:101], v[100:101], v[100:101]
	v_pk_mul_f32 v[102:103], v[96:97], v[96:97]
	v_pk_mul_f32 v[106:107], v[98:99], v[98:99]
	v_cvt_pk_bf16_f32 v96, v100, v101
	v_cvt_pk_bf16_f32 v97, v102, v103
	v_cvt_pk_bf16_f32 v98, v104, v105
	v_cvt_pk_bf16_f32 v99, v106, v107
	v_max_f32_e32 v88, 0, v88
	v_max_f32_e32 v89, 0, v89
	v_lshl_add_u64 v[202:203], v[108:109], 0, s[98:99]
	global_store_dwordx4 v[202:203], v[96:99], off
	s_nop 1
	v_or_b32_e32 v96, 32, v150
	v_pk_mul_f32 v[98:99], v[88:89], v[88:89]
	v_ashrrev_i32_e32 v97, 31, v96
	v_max_f32_e32 v92, 0, v92
	v_max_f32_e32 v93, 0, v93
	v_max_f32_e32 v90, 0, v90
	v_lshlrev_b64 v[96:97], 6, v[96:97]
	v_pk_mul_f32 v[92:93], v[92:93], v[92:93]
	v_max_f32_e32 v88, 0, v94
	v_max_f32_e32 v89, 0, v95
	v_max_f32_e32 v91, 0, v91
	v_pk_mul_f32 v[94:95], v[88:89], v[88:89]
	v_pk_mul_f32 v[100:101], v[90:91], v[90:91]
	v_cvt_pk_bf16_f32 v88, v92, v93
	v_lshl_add_u64 v[92:93], s[78:79], 0, v[96:97]
	v_cvt_pk_bf16_f32 v89, v94, v95
	v_cvt_pk_bf16_f32 v90, v98, v99
	v_cvt_pk_bf16_f32 v91, v100, v101
	v_lshl_add_u64 v[92:93], v[92:93], 0, v[126:127]
	v_max_f32_e32 v80, 0, v80
	v_max_f32_e32 v81, 0, v81
	global_store_dwordx4 v[92:93], v[88:91], off
	s_nop 1
	v_pk_mul_f32 v[88:89], v[80:81], v[80:81]
	v_max_f32_e32 v82, 0, v82
	v_max_f32_e32 v84, 0, v84
	v_max_f32_e32 v85, 0, v85
	v_max_f32_e32 v80, 0, v86
	v_max_f32_e32 v81, 0, v87
	v_max_f32_e32 v83, 0, v83
	v_pk_mul_f32 v[84:85], v[84:85], v[84:85]
	v_pk_mul_f32 v[86:87], v[80:81], v[80:81]
	v_pk_mul_f32 v[90:91], v[82:83], v[82:83]
	v_cvt_pk_bf16_f32 v80, v84, v85
	v_cvt_pk_bf16_f32 v81, v86, v87
	v_cvt_pk_bf16_f32 v82, v88, v89
	v_cvt_pk_bf16_f32 v83, v90, v91
	v_max_f32_e32 v72, 0, v72
	v_max_f32_e32 v73, 0, v73
	v_lshl_add_u64 v[204:205], v[92:93], 0, s[98:99]
	global_store_dwordx4 v[204:205], v[80:83], off
	s_nop 1
	v_or_b32_e32 v80, 48, v150
	v_pk_mul_f32 v[82:83], v[72:73], v[72:73]
	v_ashrrev_i32_e32 v81, 31, v80
	v_max_f32_e32 v76, 0, v76
	v_max_f32_e32 v77, 0, v77
	v_max_f32_e32 v74, 0, v74
	v_lshlrev_b64 v[80:81], 6, v[80:81]
	v_pk_mul_f32 v[76:77], v[76:77], v[76:77]
	v_max_f32_e32 v72, 0, v78
	v_max_f32_e32 v73, 0, v79
	v_max_f32_e32 v75, 0, v75
	v_pk_mul_f32 v[78:79], v[72:73], v[72:73]
	v_pk_mul_f32 v[84:85], v[74:75], v[74:75]
	v_cvt_pk_bf16_f32 v72, v76, v77
	v_lshl_add_u64 v[76:77], s[78:79], 0, v[80:81]
	v_cvt_pk_bf16_f32 v73, v78, v79
	v_cvt_pk_bf16_f32 v74, v82, v83
	v_cvt_pk_bf16_f32 v75, v84, v85
	v_lshl_add_u64 v[76:77], v[76:77], 0, v[126:127]
	v_max_f32_e32 v64, 0, v64
	v_max_f32_e32 v65, 0, v65
	global_store_dwordx4 v[76:77], v[72:75], off
	s_nop 1
	v_pk_mul_f32 v[72:73], v[64:65], v[64:65]
	v_max_f32_e32 v66, 0, v66
	v_max_f32_e32 v68, 0, v68
	v_max_f32_e32 v69, 0, v69
	v_max_f32_e32 v64, 0, v70
	v_max_f32_e32 v65, 0, v71
	v_max_f32_e32 v67, 0, v67
	v_pk_mul_f32 v[68:69], v[68:69], v[68:69]
	v_pk_mul_f32 v[70:71], v[64:65], v[64:65]
	v_pk_mul_f32 v[74:75], v[66:67], v[66:67]
	v_cvt_pk_bf16_f32 v64, v68, v69
	v_cvt_pk_bf16_f32 v65, v70, v71
	v_cvt_pk_bf16_f32 v66, v72, v73
	v_cvt_pk_bf16_f32 v67, v74, v75
	v_max_f32_e32 v56, 0, v56
	v_max_f32_e32 v57, 0, v57
	v_lshl_add_u64 v[206:207], v[76:77], 0, s[98:99]
	global_store_dwordx4 v[206:207], v[64:67], off
	s_nop 1
	v_pk_mul_f32 v[64:65], v[56:57], v[56:57]
	v_max_f32_e32 v58, 0, v58
	v_max_f32_e32 v56, 0, v62
	v_max_f32_e32 v57, 0, v63
	v_max_f32_e32 v60, 0, v60
	v_max_f32_e32 v61, 0, v61
	v_max_f32_e32 v59, 0, v59
	v_pk_mul_f32 v[62:63], v[56:57], v[56:57]
	v_pk_mul_f32 v[60:61], v[60:61], v[60:61]
	v_pk_mul_f32 v[66:67], v[58:59], v[58:59]
	v_cvt_pk_bf16_f32 v227, v62, v63
	v_cvt_pk_bf16_f32 v226, v60, v61
	v_cvt_pk_bf16_f32 v228, v64, v65
	v_cvt_pk_bf16_f32 v229, v66, v67
	v_max_f32_e32 v48, 0, v48
	v_max_f32_e32 v49, 0, v49
	v_pk_mul_f32 v[56:57], v[48:49], v[48:49]
	v_max_f32_e32 v50, 0, v50
	v_max_f32_e32 v52, 0, v52
	v_max_f32_e32 v53, 0, v53
	v_max_f32_e32 v48, 0, v54
	v_max_f32_e32 v49, 0, v55
	v_max_f32_e32 v51, 0, v51
	v_pk_mul_f32 v[52:53], v[52:53], v[52:53]
	v_pk_mul_f32 v[54:55], v[48:49], v[48:49]
	v_pk_mul_f32 v[58:59], v[50:51], v[50:51]
	v_cvt_pk_bf16_f32 v230, v52, v53
	v_cvt_pk_bf16_f32 v231, v54, v55
	v_cvt_pk_bf16_f32 v232, v56, v57
	v_cvt_pk_bf16_f32 v233, v58, v59
	v_max_f32_e32 v40, 0, v40
	v_max_f32_e32 v41, 0, v41
	v_pk_mul_f32 v[48:49], v[40:41], v[40:41]
	v_max_f32_e32 v42, 0, v42
	v_max_f32_e32 v40, 0, v46
	v_max_f32_e32 v41, 0, v47
	v_max_f32_e32 v44, 0, v44
	v_max_f32_e32 v45, 0, v45
	v_max_f32_e32 v43, 0, v43
	v_pk_mul_f32 v[46:47], v[40:41], v[40:41]
	v_pk_mul_f32 v[44:45], v[44:45], v[44:45]
	v_pk_mul_f32 v[50:51], v[42:43], v[42:43]
	v_cvt_pk_bf16_f32 v235, v46, v47
	v_cvt_pk_bf16_f32 v234, v44, v45
	v_cvt_pk_bf16_f32 v236, v48, v49
	v_cvt_pk_bf16_f32 v237, v50, v51
	v_max_f32_e32 v32, 0, v32
	v_max_f32_e32 v33, 0, v33
	v_pk_mul_f32 v[40:41], v[32:33], v[32:33]
	v_max_f32_e32 v34, 0, v34
	v_max_f32_e32 v36, 0, v36
	v_max_f32_e32 v37, 0, v37
	v_max_f32_e32 v32, 0, v38
	v_max_f32_e32 v33, 0, v39
	v_max_f32_e32 v35, 0, v35
	v_pk_mul_f32 v[36:37], v[36:37], v[36:37]
	v_pk_mul_f32 v[38:39], v[32:33], v[32:33]
	v_pk_mul_f32 v[42:43], v[34:35], v[34:35]
	v_cvt_pk_bf16_f32 v238, v36, v37
	v_cvt_pk_bf16_f32 v239, v38, v39
	v_cvt_pk_bf16_f32 v240, v40, v41
	v_cvt_pk_bf16_f32 v241, v42, v43
	v_max_f32_e32 v24, 0, v24
	v_max_f32_e32 v25, 0, v25
	v_pk_mul_f32 v[32:33], v[24:25], v[24:25]
	v_max_f32_e32 v26, 0, v26
	v_max_f32_e32 v24, 0, v30
	v_max_f32_e32 v25, 0, v31
	v_max_f32_e32 v28, 0, v28
	v_max_f32_e32 v29, 0, v29
	v_max_f32_e32 v27, 0, v27
	v_pk_mul_f32 v[30:31], v[24:25], v[24:25]
	v_pk_mul_f32 v[28:29], v[28:29], v[28:29]
	v_pk_mul_f32 v[34:35], v[26:27], v[26:27]
	v_cvt_pk_bf16_f32 v243, v30, v31
	v_cvt_pk_bf16_f32 v242, v28, v29
	v_cvt_pk_bf16_f32 v244, v32, v33
	v_cvt_pk_bf16_f32 v245, v34, v35
	v_max_f32_e32 v16, 0, v16
	v_max_f32_e32 v17, 0, v17
	v_pk_mul_f32 v[24:25], v[16:17], v[16:17]
	v_max_f32_e32 v18, 0, v18
	v_max_f32_e32 v20, 0, v20
	v_max_f32_e32 v21, 0, v21
	v_max_f32_e32 v16, 0, v22
	v_max_f32_e32 v17, 0, v23
	v_max_f32_e32 v19, 0, v19
	v_pk_mul_f32 v[20:21], v[20:21], v[20:21]
	v_pk_mul_f32 v[22:23], v[16:17], v[16:17]
	v_pk_mul_f32 v[26:27], v[18:19], v[18:19]
	v_cvt_pk_bf16_f32 v246, v20, v21
	v_cvt_pk_bf16_f32 v247, v22, v23
	v_cvt_pk_bf16_f32 v248, v24, v25
	v_cvt_pk_bf16_f32 v249, v26, v27
	v_max_f32_e32 v8, 0, v8
	v_max_f32_e32 v9, 0, v9
	v_pk_mul_f32 v[16:17], v[8:9], v[8:9]
	v_max_f32_e32 v10, 0, v10
	v_max_f32_e32 v8, 0, v14
	v_max_f32_e32 v9, 0, v15
	v_max_f32_e32 v12, 0, v12
	v_max_f32_e32 v13, 0, v13
	v_max_f32_e32 v11, 0, v11
	v_pk_mul_f32 v[14:15], v[8:9], v[8:9]
	v_pk_mul_f32 v[12:13], v[12:13], v[12:13]
	v_pk_mul_f32 v[18:19], v[10:11], v[10:11]
	v_cvt_pk_bf16_f32 v251, v14, v15
	v_cvt_pk_bf16_f32 v250, v12, v13
	v_cvt_pk_bf16_f32 v252, v16, v17
	v_cvt_pk_bf16_f32 v253, v18, v19
	v_max_f32_e32 v0, 0, v0
	v_max_f32_e32 v1, 0, v1
	v_pk_mul_f32 v[8:9], v[0:1], v[0:1]
	v_max_f32_e32 v2, 0, v2
	v_max_f32_e32 v4, 0, v4
	v_max_f32_e32 v5, 0, v5
	v_max_f32_e32 v0, 0, v6
	v_max_f32_e32 v1, 0, v7
	v_max_f32_e32 v3, 0, v3
	v_pk_mul_f32 v[4:5], v[4:5], v[4:5]
	v_pk_mul_f32 v[6:7], v[0:1], v[0:1]
	v_pk_mul_f32 v[10:11], v[2:3], v[2:3]
	v_cvt_pk_bf16_f32 v140, v4, v5
	v_cvt_pk_bf16_f32 v141, v6, v7
	v_cvt_pk_bf16_f32 v142, v8, v9
	v_cvt_pk_bf16_f32 v143, v10, v11
	s_andn2_b64 vcc, exec, s[4:5]
	s_mov_b64 s[4:5], -1
	s_mov_b32 s100, 1
	s_cbranch_vccnz .LBB0_869
	s_andn2_b64 vcc, exec, s[6:7]
	s_cbranch_vccnz .LBB0_868
	s_barrier
	s_branch .LBB0_868
.Lh2a_w1first:
	s_waitcnt vmcnt(17)
	s_branch .Lh2a_w1join

.Lh2a_w3first:
	s_waitcnt vmcnt(17)
	s_mov_b32 s101, 0
	s_branch .Lh2a_w3join
